# P4 K-loop: 8 of the 16 in-loop LDS-address v_add_u32 hoisted to the pre-header into v246-v253 (on top of v60)
# baseline (speedup 1.0000x reference)
; #define PG8_STAGE(bufoff, gbase, voff) do { _Pragma("unroll") for (int _i = 0; _i < 2; ++_i) \
;         __builtin_amdgcn_global_load_lds((const unsigned*)((const char*)(gbase) + (voff)[_i]), (LAS unsigned*)(lds + (bufoff) + ldsw + _i * 8192), 16, 0, 0); } while (0)
; #define PG8_LDA(dst, b, h) do { _Pragma("unroll") for (int m = 0; m < 4; ++m) _Pragma("unroll") for (int k = 0; k < 2; ++k) dst[m][k] = *(const LAS bf16x8*)(lds + PG8_SA(b, h) + aoffk[k] + m * 2048); } while (0)
; #define PG8_WAIT_V(n) asm volatile("s_waitcnt vmcnt(" #n ")" ::: "memory")
; template <class Epi, class Sched, class GemmT>
; __device__ __forceinline__ void gemm_phase(LAS unsigned char* lds, const GemmT& g, const Sched& S, const Epi& E, const int wid) {
;     ...
;         for (int sgi = 0; sgi < NSEG; ++sgi) {
;             const Seg ns = (sgi + 1 < NSEG) ? g.seg(cur, sgi + 1) : g.seg(has_next ? nxt : cur, 0);
;             unsigned nvA[2], nvB[2]; size_t nhA, nhB;
;             if constexpr (GemmT::UNIFORM) { nvA[0] = voffA[0]; nvA[1] = voffA[1]; nvB[0] = voffB[0]; nvB[1] = voffB[1]; nhA = hstepA; nhB = hstepB; }
;             else PG8_VOFFS(nvA, nvB, nhA, nhB, ns);
;             const int nt = cs.nt;
;             for (int t = 0; t < nt; t += 2) {
;                 const bool last = (t == nt - 2);
;                 const char* a1 = cA + (size_t)(t + 1) * kstep;
;                 const char* a2 = last ? ns.A : cA + (size_t)(t + 2) * kstep; const char* b2 = last ? ns.B : cB + (size_t)(t + 2) * kstep;
;                 const char* a3 = a2 + kstep; const char* b3 = b2 + kstep;
;                 unsigned vA2[2], vB2[2];
; #pragma unroll
;                 for (int i = 0; i < 2; ++i) { vA2[i] = last ? nvA[i] : voffA[i]; vB2[i] = last ? nvB[i] : voffB[i]; }
;                 const size_t hA2 = last ? nhA : hstepA, hB2 = last ? nhB : hstepB;
;                 PG8_LDB(B0, 0, 0); PG8_LDB(B1, 0, 1); PG8_SCHED; PG8_LDA(At, 0, 0); PG8_STAGE(PG8_SA(1, 1), a1 + hstepA, voffA);
;                 PG8_WAIT_V(8); PG8_WAIT_L(0); PG8_BAR; PG8_MMA(0, 0, At, B0); PG8_MMA(0, 1, At, B1); PG8_BAR; PG8_SCHED;
;                 PG8_LDA(At, 0, 1); PG8_STAGE(PG8_SB(0, 0), b2, vB2); PG8_STAGE(PG8_SB(0, 1), b2 + hB2, vB2); PG8_STAGE(PG8_SA(0, 0), a2, vA2);
;                 PG8_WAIT_V(8); PG8_WAIT_L(0); PG8_BAR; PG8_MMA(1, 0, At, B0); PG8_MMA(1, 1, At, B1); PG8_BAR; PG8_SCHED;
.LBB0_763:
	s_cmp_lg_u32 s83, 2
	s_cselect_b64 s[52:53], -1, 0
	s_cmp_eq_u32 s83, 0
	s_mov_b64 s[50:51], s[18:19]
	s_mov_b64 s[48:49], s[12:13]
	s_cselect_b32 s6, s39, s24
	s_cselect_b32 s13, s41, s25
	s_cselect_b32 s18, s16, s81
	s_cselect_b32 s19, s17, s86
	s_cmp_eq_u32 s83, 2
	s_movk_i32 s12, 0x800
	s_cselect_b32 s84, s12, 0x400
	s_cselect_b32 s12, s74, s40
	s_cselect_b32 s43, s88, s19
	s_cselect_b32 s58, s87, s18
	s_cselect_b32 s18, s75, s73
	s_cselect_b32 s59, s31, s13
	s_cselect_b32 s6, s30, s6
	s_cselect_b32 s60, 11, 10
	s_ashr_i32 s13, s12, 31
	s_lshl_b64 s[12:13], s[12:13], 8
	s_ashr_i32 s19, s18, 31
	s_lshl_b64 s[12:13], s[12:13], s60
	s_lshl_b64 s[56:57], s[18:19], 8
	s_lshl_b64 s[12:13], s[12:13], 1
	s_add_u32 s18, s58, s12
	s_addc_u32 s19, s43, s13
	s_lshl_b64 s[12:13], s[56:57], s60
	s_lshl_b64 s[12:13], s[12:13], 1
	s_add_u32 s12, s6, s12
	s_addc_u32 s13, s59, s13
	s_lshl_b32 s6, s84, 8
	s_add_u32 s85, s48, 0x100
	s_addc_u32 s89, s49, 0
	s_add_u32 s43, s50, s44
	v_lshlrev_b32_e32 v0, s60, v204
	s_addc_u32 s49, s51, s45
	v_add_lshl_u32 v190, v0, v191, 1
	v_lshlrev_b32_e32 v0, s60, v205
	s_add_u32 s48, s43, 0x80
	v_add_lshl_u32 v214, v0, v191, 1
	v_lshlrev_b32_e32 v0, s60, v206
	v_mov_b32_e32 v133, v1
	v_mov_b32_e32 v131, v1
	s_addc_u32 s49, s49, 0
	s_mov_b32 s43, s7
	v_add_lshl_u32 v194, v0, v193, 1
	v_lshlrev_b32_e32 v0, s60, v207
	v_lshl_add_u64 v[134:135], s[48:49], 0, v[132:133]
	v_lshl_add_u64 v[136:137], s[48:49], 0, v[130:131]
	s_lshl_b64 s[48:49], s[42:43], 7
	v_add_lshl_u32 v192, v0, v193, 1
	s_add_u32 s43, s48, 0xffffff00
	s_mov_b64 s[56:57], 0
	s_mov_b32 s90, 0
	v_add_u32_e32 v246, s62, v208
	v_add_u32_e32 v247, s62, v209
	v_add_u32_e32 v248, s63, v208
	v_add_u32_e32 v249, s63, v209
	v_add_u32_e32 v250, s64, v208
	v_add_u32_e32 v251, s64, v209
	v_add_u32_e32 v252, s65, v208
	v_add_u32_e32 v253, s65, v209
.LBB0_764:
	s_cmp_eq_u32 s43, s56
	s_cselect_b64 vcc, -1, 0
	s_add_i32 s90, s90, 2
	s_add_u32 s48, s50, s56
	ds_read_b128 v[144:147], v246
	ds_read_b128 v[148:151], v247
	s_addc_u32 s49, s51, s57
	ds_read_b128 v[152:155], v248
	ds_read_b128 v[156:159], v249
	s_add_u32 s58, s48, 0x100
	ds_read_b128 v[160:163], v250
	ds_read_b128 v[164:167], v251
	s_addc_u32 s59, s49, 0
	ds_read_b128 v[168:171], v252
	ds_read_b128 v[172:175], v253
	s_and_b64 s[48:49], vcc, exec
	s_cselect_b32 s59, s19, s59
	s_cselect_b32 s58, s18, s58
	s_add_u32 s60, s85, s56
	s_addc_u32 s61, s89, s57
	s_and_b64 s[48:49], vcc, exec
	v_cndmask_b32_e32 v138, v132, v190, vcc
	v_cndmask_b32_e32 v0, v143, v214, vcc
	v_cndmask_b32_e32 v140, v130, v194, vcc
	v_cndmask_b32_e32 v188, v142, v192, vcc
	s_cselect_b32 s61, s13, s61
	s_cselect_b32 s60, s12, s60
	s_cselect_b32 s91, 0, s45
	s_cselect_b32 s92, s6, s44
	v_lshl_add_u64 v[202:203], v[134:135], 0, s[56:57]
	s_add_i32 m0, s14, 0xc000
	ds_read_b128 v[176:179], v212
	ds_read_b128 v[180:183], v212 offset:2048
	ds_read_b128 v[184:187], v213
	ds_read_b128 v[216:219], v213 offset:2048
	ds_read_b128 v[220:223], v212 offset:4096
	ds_read_b128 v[224:227], v212 offset:6144
	ds_read_b128 v[230:233], v213 offset:4096
	ds_read_b128 v[234:237], v213 offset:6144
	global_load_lds_dwordx4 v[202:203], off
	v_lshl_add_u64 v[202:203], v[136:137], 0, s[56:57]
	s_add_i32 m0, s14, 0xe000
	s_nop 0
	global_load_lds_dwordx4 v[202:203], off
	s_waitcnt vmcnt(8)
	s_waitcnt lgkmcnt(0)
	s_waitcnt lgkmcnt(0)
	v_mfma_f32_16x16x32_bf16 v[126:129], v[144:147], v[176:179], v[126:129]
	v_mfma_f32_16x16x32_bf16 v[126:129], v[148:151], v[184:187], v[126:129]
	v_mfma_f32_16x16x32_bf16 v[122:125], v[156:159], v[184:187], v[122:125]
	v_mfma_f32_16x16x32_bf16 v[122:125], v[152:155], v[176:179], v[122:125]
	s_barrier
	s_setprio 3
	v_mfma_f32_16x16x32_bf16 v[106:109], v[152:155], v[180:183], v[106:109]
	v_mfma_f32_16x16x32_bf16 v[106:109], v[156:159], v[216:219], v[106:109]
	v_mfma_f32_16x16x32_bf16 v[110:113], v[148:151], v[216:219], v[110:113]
	v_mfma_f32_16x16x32_bf16 v[110:113], v[144:147], v[180:183], v[110:113]
	v_mfma_f32_16x16x32_bf16 v[94:97], v[144:147], v[220:223], v[94:97]
	v_mfma_f32_16x16x32_bf16 v[94:97], v[148:151], v[230:233], v[94:97]
	v_mfma_f32_16x16x32_bf16 v[90:93], v[156:159], v[230:233], v[90:93]
	v_mfma_f32_16x16x32_bf16 v[90:93], v[152:155], v[220:223], v[90:93]
	v_mfma_f32_16x16x32_bf16 v[74:77], v[152:155], v[224:227], v[74:77]
	v_mfma_f32_16x16x32_bf16 v[74:77], v[156:159], v[234:237], v[74:77]
	v_mfma_f32_16x16x32_bf16 v[78:81], v[148:151], v[234:237], v[78:81]
	v_mfma_f32_16x16x32_bf16 v[78:81], v[144:147], v[224:227], v[78:81]
	s_setprio 0
	s_setprio 3
	v_mfma_f32_16x16x32_bf16 v[118:121], v[160:163], v[176:179], v[118:121]
	v_mfma_f32_16x16x32_bf16 v[118:121], v[164:167], v[184:187], v[118:121]
	v_mfma_f32_16x16x32_bf16 v[114:117], v[172:175], v[184:187], v[114:117]
	v_mfma_f32_16x16x32_bf16 v[114:117], v[168:171], v[176:179], v[114:117]
	v_mfma_f32_16x16x32_bf16 v[98:101], v[168:171], v[180:183], v[98:101]
	v_mfma_f32_16x16x32_bf16 v[98:101], v[172:175], v[216:219], v[98:101]
	v_mfma_f32_16x16x32_bf16 v[102:105], v[164:167], v[216:219], v[102:105]
	v_mfma_f32_16x16x32_bf16 v[102:105], v[160:163], v[180:183], v[102:105]
	v_mfma_f32_16x16x32_bf16 v[86:89], v[160:163], v[220:223], v[86:89]
	v_mfma_f32_16x16x32_bf16 v[86:89], v[164:167], v[230:233], v[86:89]
	v_mfma_f32_16x16x32_bf16 v[82:85], v[172:175], v[230:233], v[82:85]
	v_mfma_f32_16x16x32_bf16 v[82:85], v[168:171], v[220:223], v[82:85]
	v_mfma_f32_16x16x32_bf16 v[66:69], v[168:171], v[224:227], v[66:69]
	v_mfma_f32_16x16x32_bf16 v[66:69], v[172:175], v[234:237], v[66:69]
	v_mfma_f32_16x16x32_bf16 v[70:73], v[164:167], v[234:237], v[70:73]
	v_mfma_f32_16x16x32_bf16 v[70:73], v[160:163], v[224:227], v[70:73]
	s_setprio 0
	s_barrier
; #define PG8_STAGE(bufoff, gbase, voff) do { _Pragma("unroll") for (int _i = 0; _i < 2; ++_i) \
;         __builtin_amdgcn_global_load_lds((const unsigned*)((const char*)(gbase) + (voff)[_i]), (LAS unsigned*)(lds + (bufoff) + ldsw + _i * 8192), 16, 0, 0); } while (0)
; #define PG8_LDA(dst, b, h) do { _Pragma("unroll") for (int m = 0; m < 4; ++m) _Pragma("unroll") for (int k = 0; k < 2; ++k) dst[m][k] = *(const LAS bf16x8*)(lds + PG8_SA(b, h) + aoffk[k] + m * 2048); } while (0)
; #define PG8_LDB(dst, b, h) do { _Pragma("unroll") for (int n = 0; n < 2; ++n) _Pragma("unroll") for (int k = 0; k < 2; ++k) dst[n][k] = *(const LAS bf16x8*)(lds + PG8_SB(b, h) + boffk[k] + n * 2048); } while (0)
; #define PG8_WAIT_V(n) asm volatile("s_waitcnt vmcnt(" #n ")" ::: "memory")
; #define PG8_WAIT_L(n) asm volatile("s_waitcnt lgkmcnt(" #n ")" ::: "memory")
; #define PG8_BAR __builtin_amdgcn_s_barrier()
; #define PG8_SCHED __builtin_amdgcn_sched_barrier(0)
; template <class Epi, class Sched, class GemmT>
; __device__ __forceinline__ void gemm_phase(LAS unsigned char* lds, const GemmT& g, const Sched& S, const Epi& E, const int wid) {
;     ...
;                 PG8_LDA(At, 0, 1); PG8_STAGE(PG8_SB(0, 0), b2, vB2); PG8_STAGE(PG8_SB(0, 1), b2 + hB2, vB2); PG8_STAGE(PG8_SA(0, 0), a2, vA2);
;                 PG8_WAIT_V(8); PG8_WAIT_L(0); PG8_BAR; PG8_MMA(1, 0, At, B0); PG8_MMA(1, 1, At, B1); PG8_BAR; PG8_SCHED;
;                 PG8_LDB(B0, 1, 0); PG8_LDB(B1, 1, 1); PG8_SCHED; PG8_LDA(At, 1, 0); PG8_STAGE(PG8_SA(0, 1), a2 + hA2, vA2);
;                 PG8_WAIT_V(8); PG8_WAIT_L(0); PG8_BAR; PG8_MMA(0, 0, At, B0); PG8_MMA(0, 1, At, B1); PG8_BAR; PG8_SCHED;
;                 PG8_LDA(At, 1, 1); PG8_STAGE(PG8_SB(1, 0), b3, vB2); PG8_STAGE(PG8_SB(1, 1), b3 + hB2, vB2); PG8_STAGE(PG8_SA(1, 0), a3, vA2);
	s_add_i32 s48, s62, s68
	s_mov_b32 m0, s48
	ds_read_b128 v[176:179], v212 offset:16384
	ds_read_b128 v[180:183], v213 offset:16384
	ds_read_b128 v[184:187], v212 offset:18432
	ds_read_b128 v[216:219], v213 offset:18432
	ds_read_b128 v[220:223], v212 offset:20480
	ds_read_b128 v[224:227], v213 offset:20480
	ds_read_b128 v[230:233], v212 offset:22528
	ds_read_b128 v[234:237], v213 offset:22528
	global_load_lds_dwordx4 v0, s[60:61]
	s_add_i32 m0, s48, 0x2000
	v_mov_b32_e32 v189, v1
	s_add_u32 s48, s60, s92
	v_lshl_add_u64 v[202:203], s[60:61], 0, v[0:1]
	v_lshl_add_u64 v[238:239], s[60:61], 0, v[188:189]
	global_load_lds_dwordx4 v188, s[60:61]
	s_addc_u32 s49, s61, s91
	s_add_i32 s60, s64, s68
	s_mov_b32 m0, s60
	v_mov_b32_e32 v139, v1
	global_load_lds_dwordx4 v0, s[48:49]
	s_add_i32 m0, s60, 0x2000
	v_mov_b32_e32 v141, v1
	global_load_lds_dwordx4 v188, s[48:49]
	s_mov_b32 m0, s14
	v_lshl_add_u64 v[240:241], s[48:49], 0, v[0:1]
	global_load_lds_dwordx4 v138, s[58:59]
	s_mov_b32 m0, s15
	v_lshl_add_u64 v[242:243], s[48:49], 0, v[188:189]
	global_load_lds_dwordx4 v140, s[58:59]
	s_waitcnt vmcnt(8)
	s_waitcnt lgkmcnt(0)
	v_lshl_add_u64 v[188:189], s[58:59], 0, v[138:139]
	v_lshl_add_u64 v[244:245], s[58:59], 0, v[140:141]
	s_waitcnt lgkmcnt(0)
	v_mfma_f32_16x16x32_bf16 v[62:65], v[144:147], v[176:179], v[62:65]
	v_mfma_f32_16x16x32_bf16 v[62:65], v[148:151], v[180:183], v[62:65]
	v_mfma_f32_16x16x32_bf16 v[58:61], v[156:159], v[180:183], v[58:61]
	v_mfma_f32_16x16x32_bf16 v[58:61], v[152:155], v[176:179], v[58:61]
	s_barrier
	s_setprio 3
	v_mfma_f32_16x16x32_bf16 v[42:45], v[152:155], v[184:187], v[42:45]
	v_mfma_f32_16x16x32_bf16 v[42:45], v[156:159], v[216:219], v[42:45]
	v_mfma_f32_16x16x32_bf16 v[46:49], v[148:151], v[216:219], v[46:49]
	v_mfma_f32_16x16x32_bf16 v[46:49], v[144:147], v[184:187], v[46:49]
	v_mfma_f32_16x16x32_bf16 v[30:33], v[144:147], v[220:223], v[30:33]
	v_mfma_f32_16x16x32_bf16 v[30:33], v[148:151], v[224:227], v[30:33]
	v_mfma_f32_16x16x32_bf16 v[22:25], v[156:159], v[224:227], v[22:25]
	v_mfma_f32_16x16x32_bf16 v[22:25], v[152:155], v[220:223], v[22:25]
	v_mfma_f32_16x16x32_bf16 v[6:9], v[152:155], v[230:233], v[6:9]
	v_mfma_f32_16x16x32_bf16 v[6:9], v[156:159], v[234:237], v[6:9]
	v_mfma_f32_16x16x32_bf16 v[14:17], v[148:151], v[234:237], v[14:17]
	v_mfma_f32_16x16x32_bf16 v[14:17], v[144:147], v[230:233], v[14:17]
	s_setprio 0
	s_setprio 3
	v_mfma_f32_16x16x32_bf16 v[54:57], v[160:163], v[176:179], v[54:57]
	v_mfma_f32_16x16x32_bf16 v[54:57], v[164:167], v[180:183], v[54:57]
	v_mfma_f32_16x16x32_bf16 v[50:53], v[172:175], v[180:183], v[50:53]
	v_mfma_f32_16x16x32_bf16 v[50:53], v[168:171], v[176:179], v[50:53]
	v_mfma_f32_16x16x32_bf16 v[34:37], v[168:171], v[184:187], v[34:37]
	v_mfma_f32_16x16x32_bf16 v[34:37], v[172:175], v[216:219], v[34:37]
	v_mfma_f32_16x16x32_bf16 v[38:41], v[164:167], v[216:219], v[38:41]
	v_mfma_f32_16x16x32_bf16 v[38:41], v[160:163], v[184:187], v[38:41]
	v_mfma_f32_16x16x32_bf16 v[26:29], v[160:163], v[220:223], v[26:29]
	v_mfma_f32_16x16x32_bf16 v[26:29], v[164:167], v[224:227], v[26:29]
	v_mfma_f32_16x16x32_bf16 v[18:21], v[172:175], v[224:227], v[18:21]
	v_mfma_f32_16x16x32_bf16 v[18:21], v[168:171], v[220:223], v[18:21]
	v_mfma_f32_16x16x32_bf16 v[2:5], v[168:171], v[230:233], v[2:5]
	v_mfma_f32_16x16x32_bf16 v[2:5], v[172:175], v[234:237], v[2:5]
	v_mfma_f32_16x16x32_bf16 v[10:13], v[164:167], v[234:237], v[10:13]
	v_mfma_f32_16x16x32_bf16 v[10:13], v[160:163], v[230:233], v[10:13]
	s_setprio 0
	s_barrier
	s_add_i32 s60, 0, 0x18000
	v_add_u32_e32 v0, s60, v208
	v_add_u32_e32 v131, s60, v209
	ds_read_b128 v[144:147], v0
	ds_read_b128 v[148:151], v131
	v_add_u32_e32 v0, s66, v208
	s_add_i32 s61, 0, 0x1c000
	v_add_u32_e32 v131, s66, v209
	ds_read_b128 v[152:155], v0
	ds_read_b128 v[156:159], v131
	v_add_u32_e32 v0, s61, v208
	v_add_u32_e32 v131, s61, v209
	ds_read_b128 v[160:163], v0
	ds_read_b128 v[164:167], v131
	v_add_u32_e32 v0, s67, v208
	v_add_u32_e32 v131, s67, v209
	ds_read_b128 v[168:171], v0
	ds_read_b128 v[172:175], v131
	s_add_u32 s48, s58, s92
	s_addc_u32 s49, s59, s91
	s_mov_b32 m0, s34
	ds_read_b128 v[176:179], v212 offset:32768
	ds_read_b128 v[180:183], v212 offset:34816
	ds_read_b128 v[184:187], v213 offset:32768
	ds_read_b128 v[216:219], v213 offset:34816
	ds_read_b128 v[220:223], v212 offset:36864
	ds_read_b128 v[224:227], v212 offset:38912
	ds_read_b128 v[230:233], v213 offset:36864
	ds_read_b128 v[234:237], v213 offset:38912
	global_load_lds_dwordx4 v138, s[48:49]
	s_mov_b32 m0, s35
	s_nop 0
	global_load_lds_dwordx4 v140, s[48:49]
	s_waitcnt vmcnt(8)
	s_waitcnt lgkmcnt(0)
	s_waitcnt lgkmcnt(0)
	v_mfma_f32_16x16x32_bf16 v[126:129], v[144:147], v[176:179], v[126:129]
	v_mfma_f32_16x16x32_bf16 v[126:129], v[148:151], v[184:187], v[126:129]
	v_mfma_f32_16x16x32_bf16 v[122:125], v[156:159], v[184:187], v[122:125]
	v_mfma_f32_16x16x32_bf16 v[122:125], v[152:155], v[176:179], v[122:125]
	s_barrier
; #define PG8_STAGE(bufoff, gbase, voff) do { _Pragma("unroll") for (int _i = 0; _i < 2; ++_i) \
;         __builtin_amdgcn_global_load_lds((const unsigned*)((const char*)(gbase) + (voff)[_i]), (LAS unsigned*)(lds + (bufoff) + ldsw + _i * 8192), 16, 0, 0); } while (0)
; #define PG8_LDA(dst, b, h) do { _Pragma("unroll") for (int m = 0; m < 4; ++m) _Pragma("unroll") for (int k = 0; k < 2; ++k) dst[m][k] = *(const LAS bf16x8*)(lds + PG8_SA(b, h) + aoffk[k] + m * 2048); } while (0)
; #define PG8_WAIT_V(n) asm volatile("s_waitcnt vmcnt(" #n ")" ::: "memory")
; #define PG8_WAIT_L(n) asm volatile("s_waitcnt lgkmcnt(" #n ")" ::: "memory")
; #define PG8_BAR __builtin_amdgcn_s_barrier()
; #define PG8_SCHED __builtin_amdgcn_sched_barrier(0)
; template <class Epi, class Sched, class GemmT>
; __device__ __forceinline__ void gemm_phase(LAS unsigned char* lds, const GemmT& g, const Sched& S, const Epi& E, const int wid) {
;     ...
;                 PG8_LDA(At, 1, 1); PG8_STAGE(PG8_SB(1, 0), b3, vB2); PG8_STAGE(PG8_SB(1, 1), b3 + hB2, vB2); PG8_STAGE(PG8_SA(1, 0), a3, vA2);
;                 PG8_WAIT_V(8); PG8_WAIT_L(0); PG8_BAR; PG8_MMA(1, 0, At, B0); PG8_MMA(1, 1, At, B1); PG8_BAR; PG8_SCHED;
;             }
;             if constexpr (NSEG > 1) { if (sgi + 1 < NSEG) E.mid(acc, cur, sgi, wr, wc, fr, fq); }
	s_setprio 3
	v_mfma_f32_16x16x32_bf16 v[106:109], v[152:155], v[180:183], v[106:109]
	v_mfma_f32_16x16x32_bf16 v[106:109], v[156:159], v[216:219], v[106:109]
	v_mfma_f32_16x16x32_bf16 v[110:113], v[148:151], v[216:219], v[110:113]
	v_mfma_f32_16x16x32_bf16 v[110:113], v[144:147], v[180:183], v[110:113]
	v_mfma_f32_16x16x32_bf16 v[94:97], v[144:147], v[220:223], v[94:97]
	v_mfma_f32_16x16x32_bf16 v[94:97], v[148:151], v[230:233], v[94:97]
	v_mfma_f32_16x16x32_bf16 v[90:93], v[156:159], v[230:233], v[90:93]
	v_mfma_f32_16x16x32_bf16 v[90:93], v[152:155], v[220:223], v[90:93]
	v_mfma_f32_16x16x32_bf16 v[74:77], v[152:155], v[224:227], v[74:77]
	v_mfma_f32_16x16x32_bf16 v[74:77], v[156:159], v[234:237], v[74:77]
	v_mfma_f32_16x16x32_bf16 v[78:81], v[148:151], v[234:237], v[78:81]
	v_mfma_f32_16x16x32_bf16 v[78:81], v[144:147], v[224:227], v[78:81]
	s_setprio 0
	s_setprio 3
	v_mfma_f32_16x16x32_bf16 v[118:121], v[160:163], v[176:179], v[118:121]
	v_mfma_f32_16x16x32_bf16 v[118:121], v[164:167], v[184:187], v[118:121]
	v_mfma_f32_16x16x32_bf16 v[114:117], v[172:175], v[184:187], v[114:117]
	v_mfma_f32_16x16x32_bf16 v[114:117], v[168:171], v[176:179], v[114:117]
	v_mfma_f32_16x16x32_bf16 v[98:101], v[168:171], v[180:183], v[98:101]
	v_mfma_f32_16x16x32_bf16 v[98:101], v[172:175], v[216:219], v[98:101]
	v_mfma_f32_16x16x32_bf16 v[102:105], v[164:167], v[216:219], v[102:105]
	v_mfma_f32_16x16x32_bf16 v[102:105], v[160:163], v[180:183], v[102:105]
	v_mfma_f32_16x16x32_bf16 v[86:89], v[160:163], v[220:223], v[86:89]
	v_mfma_f32_16x16x32_bf16 v[86:89], v[164:167], v[230:233], v[86:89]
	v_mfma_f32_16x16x32_bf16 v[82:85], v[172:175], v[230:233], v[82:85]
	v_mfma_f32_16x16x32_bf16 v[82:85], v[168:171], v[220:223], v[82:85]
	v_mfma_f32_16x16x32_bf16 v[66:69], v[168:171], v[224:227], v[66:69]
	v_mfma_f32_16x16x32_bf16 v[66:69], v[172:175], v[234:237], v[66:69]
	v_mfma_f32_16x16x32_bf16 v[70:73], v[164:167], v[234:237], v[70:73]
	v_mfma_f32_16x16x32_bf16 v[70:73], v[160:163], v[224:227], v[70:73]
	s_setprio 0
	s_barrier
	s_add_i32 s48, s60, s68
	v_lshl_add_u64 v[202:203], v[202:203], 0, s[20:21]
	s_mov_b32 m0, s48
	ds_read_b128 v[138:141], v212 offset:49152
	ds_read_b128 v[176:179], v212 offset:51200
	ds_read_b128 v[180:183], v213 offset:49152
	ds_read_b128 v[184:187], v213 offset:51200
	ds_read_b128 v[216:219], v212 offset:53248
	ds_read_b128 v[220:223], v212 offset:55296
	ds_read_b128 v[224:227], v213 offset:53248
	ds_read_b128 v[230:233], v213 offset:55296
	global_load_lds_dwordx4 v[202:203], off
	v_lshl_add_u64 v[202:203], v[238:239], 0, s[20:21]
	s_add_i32 m0, s48, 0x2000
	s_add_i32 s48, s61, s68
	global_load_lds_dwordx4 v[202:203], off
	v_lshl_add_u64 v[202:203], v[240:241], 0, s[20:21]
	s_mov_b32 m0, s48
	v_lshl_add_u64 v[188:189], v[188:189], 0, s[20:21]
	global_load_lds_dwordx4 v[202:203], off
	v_lshl_add_u64 v[202:203], v[242:243], 0, s[20:21]
	s_add_i32 m0, s48, 0x2000
	s_nop 0
	global_load_lds_dwordx4 v[202:203], off
	s_mov_b32 m0, s54
	s_nop 0
	global_load_lds_dwordx4 v[188:189], off
	v_lshl_add_u64 v[188:189], v[244:245], 0, s[20:21]
	s_mov_b32 m0, s55
	s_nop 0
	global_load_lds_dwordx4 v[188:189], off
	s_waitcnt vmcnt(8)
	s_waitcnt lgkmcnt(0)
	s_waitcnt lgkmcnt(0)
	v_mfma_f32_16x16x32_bf16 v[62:65], v[144:147], v[138:141], v[62:65]
	v_mfma_f32_16x16x32_bf16 v[62:65], v[148:151], v[180:183], v[62:65]
	v_mfma_f32_16x16x32_bf16 v[58:61], v[156:159], v[180:183], v[58:61]
	v_mfma_f32_16x16x32_bf16 v[58:61], v[152:155], v[138:141], v[58:61]
	s_barrier
	s_setprio 3
	v_mfma_f32_16x16x32_bf16 v[42:45], v[152:155], v[176:179], v[42:45]
	v_mfma_f32_16x16x32_bf16 v[42:45], v[156:159], v[184:187], v[42:45]
	v_mfma_f32_16x16x32_bf16 v[46:49], v[148:151], v[184:187], v[46:49]
	v_mfma_f32_16x16x32_bf16 v[46:49], v[144:147], v[176:179], v[46:49]
	v_mfma_f32_16x16x32_bf16 v[30:33], v[144:147], v[216:219], v[30:33]
	v_mfma_f32_16x16x32_bf16 v[30:33], v[148:151], v[224:227], v[30:33]
	v_mfma_f32_16x16x32_bf16 v[22:25], v[156:159], v[224:227], v[22:25]
	v_mfma_f32_16x16x32_bf16 v[22:25], v[152:155], v[216:219], v[22:25]
	v_mfma_f32_16x16x32_bf16 v[6:9], v[152:155], v[220:223], v[6:9]
	v_mfma_f32_16x16x32_bf16 v[6:9], v[156:159], v[230:233], v[6:9]
	v_mfma_f32_16x16x32_bf16 v[14:17], v[148:151], v[230:233], v[14:17]
	v_mfma_f32_16x16x32_bf16 v[14:17], v[144:147], v[220:223], v[14:17]
	s_setprio 0
	s_setprio 3
	v_mfma_f32_16x16x32_bf16 v[54:57], v[160:163], v[138:141], v[54:57]
	v_mfma_f32_16x16x32_bf16 v[54:57], v[164:167], v[180:183], v[54:57]
	v_mfma_f32_16x16x32_bf16 v[50:53], v[172:175], v[180:183], v[50:53]
	v_mfma_f32_16x16x32_bf16 v[50:53], v[168:171], v[138:141], v[50:53]
	v_mfma_f32_16x16x32_bf16 v[34:37], v[168:171], v[176:179], v[34:37]
	v_mfma_f32_16x16x32_bf16 v[34:37], v[172:175], v[184:187], v[34:37]
	v_mfma_f32_16x16x32_bf16 v[38:41], v[164:167], v[184:187], v[38:41]
	v_mfma_f32_16x16x32_bf16 v[38:41], v[160:163], v[176:179], v[38:41]
	v_mfma_f32_16x16x32_bf16 v[26:29], v[160:163], v[216:219], v[26:29]
	v_mfma_f32_16x16x32_bf16 v[26:29], v[164:167], v[224:227], v[26:29]
	v_mfma_f32_16x16x32_bf16 v[18:21], v[172:175], v[224:227], v[18:21]
	v_mfma_f32_16x16x32_bf16 v[18:21], v[168:171], v[216:219], v[18:21]
	v_mfma_f32_16x16x32_bf16 v[2:5], v[168:171], v[220:223], v[2:5]
	v_mfma_f32_16x16x32_bf16 v[2:5], v[172:175], v[230:233], v[2:5]
	v_mfma_f32_16x16x32_bf16 v[10:13], v[164:167], v[230:233], v[10:13]
	v_mfma_f32_16x16x32_bf16 v[10:13], v[160:163], v[220:223], v[10:13]
	s_setprio 0
	s_add_u32 s56, s56, 0x100
	s_addc_u32 s57, s57, 0
	s_cmp_ge_u32 s90, s42
	s_barrier
	s_cbranch_scc0 .LBB0_764
	s_and_b64 vcc, exec, s[52:53]
	s_cbranch_vccz .LBB0_767
;     __device__ __forceinline__ void mid(Acc& acc, const Unit& u, int s, int wr, int wc, int fr, int fq) const {
;         int lo = (wr * 4 + wc) * 8192 + (fq * 16 + fr) * 16; asm volatile("" : "+v"(lo));
;         const unsigned char* gp = gate + ((size_t)(u.pm * 48 + s * 16 + u.pn) << 16) + lo;
;         u32x4 G[8][2];
; #pragma unroll
;         for (int i = 0; i < 8; ++i) { G[i][0] = __builtin_nontemporal_load((const u32x4*)(gp + i * 1024)); G[i][1] = __builtin_nontemporal_load((const u32x4*)(gp + (1 << 20) + i * 1024)); }
; #pragma unroll
;         for (int i = 0; i < 8; ++i) { const int ai = i >> 2, m = i & 3;
; #pragma unroll
;             for (int bj = 0; bj < 2; ++bj) {
;                 const u32x4 ga = G[i][0], gb = G[i][1];
;                 const u32x2 wa = bj == 0 ? (u32x2){ga.x, ga.y} : (u32x2){ga.z, ga.w}, wb = bj == 0 ? (u32x2){gb.x, gb.y} : (u32x2){gb.z, gb.w};
;                 float fa[8], fb[8]; gate_unpack8(wa, fa); gate_unpack8(wb, fb);
; #pragma unroll
;                 for (int e = 0; e < 8; ++e) fa[e] = fa[e] * __builtin_amdgcn_rcpf(fb[e]);
;                 f32x4& v0 = acc[ai][bj][m][0]; f32x4& v1 = acc[ai][bj][m][1];
;                 v0[0] *= fa[0]; v0[1] *= fa[1]; v0[2] *= fa[2]; v0[3] *= fa[3]; v1[0] *= fa[4]; v1[1] *= fa[5]; v1[2] *= fa[6]; v1[3] *= fa[7]; }
;             __builtin_amdgcn_sched_barrier(0); }
	s_lshl_b32 s42, s83, 4
	s_add_i32 s42, s82, s42
	s_ashr_i32 s43, s42, 31
	s_lshl_b64 s[42:43], s[42:43], 16
	v_mov_b32_e32 v130, v210
	s_add_u32 s42, s22, s42
	s_addc_u32 s43, s23, s43
	v_ashrrev_i32_e32 v131, 31, v130
	v_lshl_add_u64 v[130:131], s[42:43], 0, v[130:131]
	v_add_co_u32_e32 v132, vcc, s69, v130
	s_mov_b32 s42, 0x101000
	s_nop 0
	v_addc_co_u32_e32 v133, vcc, 0, v131, vcc
	global_load_dwordx4 v[186:189], v[130:131], off nt
	v_add_co_u32_e32 v134, vcc, s42, v130
	s_movk_i32 s42, 0x1000
	s_nop 0
	v_addc_co_u32_e32 v135, vcc, 0, v131, vcc
	global_load_dwordx4 v[216:219], v[134:135], off offset:-4096 nt
	global_load_dwordx4 v[178:181], v[130:131], off offset:1024 nt
	global_load_dwordx4 v[182:185], v[132:133], off offset:1024 nt
	global_load_dwordx4 v[170:173], v[130:131], off offset:2048 nt
	global_load_dwordx4 v[174:177], v[132:133], off offset:2048 nt
	global_load_dwordx4 v[162:165], v[130:131], off offset:3072 nt
	global_load_dwordx4 v[166:169], v[132:133], off offset:3072 nt
	v_add_co_u32_e32 v130, vcc, s42, v130
	s_waitcnt vmcnt(0)
	v_cvt_f32_ubyte0_e32 v0, v216
	v_addc_co_u32_e32 v131, vcc, 0, v131, vcc
	global_load_dwordx4 v[154:157], v[130:131], off nt
	global_load_dwordx4 v[158:161], v[134:135], off nt
	global_load_dwordx4 v[146:149], v[130:131], off offset:1024 nt
	global_load_dwordx4 v[150:153], v[134:135], off offset:1024 nt
	global_load_dwordx4 v[138:141], v[130:131], off offset:2048 nt
	global_load_dwordx4 v[142:145], v[134:135], off offset:2048 nt
	s_nop 0
	global_load_dwordx4 v[130:133], v[130:131], off offset:3072 nt
	s_nop 0
	global_load_dwordx4 v[134:137], v[134:135], off offset:3072 nt
	v_cvt_f32_ubyte1_e32 v203, v216
	v_cvt_f32_ubyte2_e32 v215, v216
	v_cvt_f32_ubyte3_e32 v220, v216
	v_cvt_f32_ubyte0_e32 v221, v217
	v_cvt_f32_ubyte1_e32 v222, v217
	v_cvt_f32_ubyte2_e32 v223, v217
	v_cvt_f32_ubyte3_e32 v224, v217
	v_rcp_iflag_f32_e32 v202, v0
	v_rcp_iflag_f32_e32 v203, v203
	v_rcp_iflag_f32_e32 v216, v215
	v_rcp_iflag_f32_e32 v217, v220
	v_rcp_iflag_f32_e32 v220, v221
	v_rcp_iflag_f32_e32 v221, v222
	v_rcp_iflag_f32_e32 v222, v223
	v_rcp_iflag_f32_e32 v223, v224
	v_cvt_f32_ubyte3_e32 v225, v186
	v_cvt_f32_ubyte2_e32 v224, v186
	v_cvt_f32_ubyte1_e32 v227, v186
	v_cvt_f32_ubyte0_e32 v226, v186
	v_pk_mul_f32 v[202:203], v[202:203], v[226:227]
	v_pk_mul_f32 v[216:217], v[216:217], v[224:225]
	v_pk_mul_f32 v[126:127], v[126:127], v[202:203]
	v_pk_mul_f32 v[128:129], v[128:129], v[216:217]
	v_cvt_f32_ubyte3_e32 v203, v187
	v_cvt_f32_ubyte2_e32 v202, v187
	v_cvt_f32_ubyte1_e32 v217, v187
	v_cvt_f32_ubyte0_e32 v216, v187
	v_pk_mul_f32 v[186:187], v[220:221], v[216:217]
	v_pk_mul_f32 v[202:203], v[222:223], v[202:203]
	v_pk_mul_f32 v[122:123], v[122:123], v[186:187]
	v_pk_mul_f32 v[124:125], v[124:125], v[202:203]
	v_cvt_f32_ubyte0_e32 v0, v218
	v_cvt_f32_ubyte1_e32 v186, v218
	v_cvt_f32_ubyte2_e32 v187, v218
	v_cvt_f32_ubyte3_e32 v202, v218
	v_cvt_f32_ubyte0_e32 v203, v219
	v_cvt_f32_ubyte1_e32 v215, v219
	v_cvt_f32_ubyte2_e32 v220, v219
	v_cvt_f32_ubyte3_e32 v221, v219
	v_rcp_iflag_f32_e32 v216, v0
	v_rcp_iflag_f32_e32 v217, v186
	v_rcp_iflag_f32_e32 v218, v187
	v_rcp_iflag_f32_e32 v219, v202
	v_rcp_iflag_f32_e32 v202, v203
	v_rcp_iflag_f32_e32 v203, v215
	v_rcp_iflag_f32_e32 v186, v220
	v_rcp_iflag_f32_e32 v187, v221
	v_cvt_f32_ubyte3_e32 v221, v188
	v_cvt_f32_ubyte2_e32 v220, v188
	v_cvt_f32_ubyte1_e32 v223, v188
	v_cvt_f32_ubyte0_e32 v222, v188
	v_pk_mul_f32 v[216:217], v[216:217], v[222:223]
	v_pk_mul_f32 v[218:219], v[218:219], v[220:221]
	v_pk_mul_f32 v[118:119], v[118:119], v[216:217]
	v_pk_mul_f32 v[120:121], v[120:121], v[218:219]
	v_cvt_f32_ubyte3_e32 v217, v189
	v_cvt_f32_ubyte2_e32 v216, v189
	v_cvt_f32_ubyte1_e32 v219, v189
	v_cvt_f32_ubyte0_e32 v218, v189
	v_pk_mul_f32 v[188:189], v[202:203], v[218:219]
	v_pk_mul_f32 v[186:187], v[186:187], v[216:217]
	v_pk_mul_f32 v[114:115], v[114:115], v[188:189]
	v_pk_mul_f32 v[116:117], v[116:117], v[186:187]
	v_cvt_f32_ubyte0_e32 v0, v182
	v_cvt_f32_ubyte1_e32 v186, v182
	v_cvt_f32_ubyte2_e32 v187, v182
	v_cvt_f32_ubyte3_e32 v188, v182
	v_cvt_f32_ubyte0_e32 v189, v183
	v_cvt_f32_ubyte1_e32 v202, v183
	v_cvt_f32_ubyte2_e32 v203, v183
	v_cvt_f32_ubyte3_e32 v215, v183
	v_rcp_iflag_f32_e32 v182, v0
	v_rcp_iflag_f32_e32 v183, v186
	v_rcp_iflag_f32_e32 v186, v187
	v_rcp_iflag_f32_e32 v187, v188
	v_rcp_iflag_f32_e32 v188, v189
	v_rcp_iflag_f32_e32 v189, v202
	v_rcp_iflag_f32_e32 v202, v203
	v_rcp_iflag_f32_e32 v203, v215
	v_cvt_f32_ubyte3_e32 v217, v178
	v_cvt_f32_ubyte2_e32 v216, v178
	v_cvt_f32_ubyte1_e32 v219, v178
	v_cvt_f32_ubyte0_e32 v218, v178
	v_pk_mul_f32 v[182:183], v[182:183], v[218:219]
	v_pk_mul_f32 v[186:187], v[186:187], v[216:217]
	v_pk_mul_f32 v[110:111], v[110:111], v[182:183]
	v_pk_mul_f32 v[112:113], v[112:113], v[186:187]
	v_cvt_f32_ubyte3_e32 v183, v179
	v_cvt_f32_ubyte2_e32 v182, v179
	v_cvt_f32_ubyte1_e32 v187, v179
	v_cvt_f32_ubyte0_e32 v186, v179
	v_pk_mul_f32 v[178:179], v[188:189], v[186:187]
	v_pk_mul_f32 v[182:183], v[202:203], v[182:183]
	v_pk_mul_f32 v[106:107], v[106:107], v[178:179]
	v_pk_mul_f32 v[108:109], v[108:109], v[182:183]
	v_cvt_f32_ubyte0_e32 v0, v184
	v_cvt_f32_ubyte1_e32 v179, v184
	v_cvt_f32_ubyte2_e32 v182, v184
	v_cvt_f32_ubyte3_e32 v183, v184
	v_rcp_iflag_f32_e32 v178, v0
	v_rcp_iflag_f32_e32 v179, v179
	v_rcp_iflag_f32_e32 v182, v182
	v_rcp_iflag_f32_e32 v183, v183
	v_cvt_f32_ubyte0_e32 v184, v185
	v_cvt_f32_ubyte1_e32 v186, v185
	v_cvt_f32_ubyte2_e32 v187, v185
	v_cvt_f32_ubyte3_e32 v188, v185
	v_rcp_iflag_f32_e32 v184, v184
	v_rcp_iflag_f32_e32 v185, v186
	v_rcp_iflag_f32_e32 v186, v187
	v_rcp_iflag_f32_e32 v187, v188
;     __device__ __forceinline__ void mid(Acc& acc, const Unit& u, int s, int wr, int wc, int fr, int fq) const {
;     ...
;         for (int i = 0; i < 8; ++i) { const int ai = i >> 2, m = i & 3;
; #pragma unroll
;             for (int bj = 0; bj < 2; ++bj) {
;                 const u32x4 ga = G[i][0], gb = G[i][1];
;                 const u32x2 wa = bj == 0 ? (u32x2){ga.x, ga.y} : (u32x2){ga.z, ga.w}, wb = bj == 0 ? (u32x2){gb.x, gb.y} : (u32x2){gb.z, gb.w};
;                 float fa[8], fb[8]; gate_unpack8(wa, fa); gate_unpack8(wb, fb);
; #pragma unroll
;                 for (int e = 0; e < 8; ++e) fa[e] = fa[e] * __builtin_amdgcn_rcpf(fb[e]);
;                 f32x4& v0 = acc[ai][bj][m][0]; f32x4& v1 = acc[ai][bj][m][1];
;                 v0[0] *= fa[0]; v0[1] *= fa[1]; v0[2] *= fa[2]; v0[3] *= fa[3]; v1[0] *= fa[4]; v1[1] *= fa[5]; v1[2] *= fa[6]; v1[3] *= fa[7]; }
;             __builtin_amdgcn_sched_barrier(0); }
	v_cvt_f32_ubyte3_e32 v189, v180
	v_cvt_f32_ubyte2_e32 v188, v180
	v_cvt_f32_ubyte1_e32 v203, v180
	v_cvt_f32_ubyte0_e32 v202, v180
	v_pk_mul_f32 v[178:179], v[178:179], v[202:203]
	v_pk_mul_f32 v[182:183], v[182:183], v[188:189]
	v_pk_mul_f32 v[102:103], v[102:103], v[178:179]
	v_pk_mul_f32 v[104:105], v[104:105], v[182:183]
	v_cvt_f32_ubyte3_e32 v179, v181
	v_cvt_f32_ubyte2_e32 v178, v181
	v_cvt_f32_ubyte1_e32 v183, v181
	v_cvt_f32_ubyte0_e32 v182, v181
	v_pk_mul_f32 v[180:181], v[184:185], v[182:183]
	v_pk_mul_f32 v[178:179], v[186:187], v[178:179]
	v_pk_mul_f32 v[98:99], v[98:99], v[180:181]
	v_pk_mul_f32 v[100:101], v[100:101], v[178:179]
	v_cvt_f32_ubyte0_e32 v0, v174
	v_cvt_f32_ubyte1_e32 v178, v174
	v_cvt_f32_ubyte2_e32 v179, v174
	v_cvt_f32_ubyte3_e32 v180, v174
	v_cvt_f32_ubyte0_e32 v181, v175
	v_cvt_f32_ubyte1_e32 v182, v175
	v_cvt_f32_ubyte2_e32 v183, v175
	v_cvt_f32_ubyte3_e32 v184, v175
	v_rcp_iflag_f32_e32 v174, v0
	v_rcp_iflag_f32_e32 v175, v178
	v_rcp_iflag_f32_e32 v178, v179
	v_rcp_iflag_f32_e32 v179, v180
	v_rcp_iflag_f32_e32 v180, v181
	v_rcp_iflag_f32_e32 v181, v182
	v_rcp_iflag_f32_e32 v182, v183
	v_rcp_iflag_f32_e32 v183, v184
	v_cvt_f32_ubyte3_e32 v185, v170
	v_cvt_f32_ubyte2_e32 v184, v170
	v_cvt_f32_ubyte1_e32 v187, v170
	v_cvt_f32_ubyte0_e32 v186, v170
	v_pk_mul_f32 v[174:175], v[174:175], v[186:187]
	v_pk_mul_f32 v[178:179], v[178:179], v[184:185]
	v_pk_mul_f32 v[94:95], v[94:95], v[174:175]
	v_pk_mul_f32 v[96:97], v[96:97], v[178:179]
	v_cvt_f32_ubyte3_e32 v175, v171
	v_cvt_f32_ubyte2_e32 v174, v171
	v_cvt_f32_ubyte1_e32 v179, v171
	v_cvt_f32_ubyte0_e32 v178, v171
	v_pk_mul_f32 v[170:171], v[180:181], v[178:179]
	v_pk_mul_f32 v[174:175], v[182:183], v[174:175]
	v_pk_mul_f32 v[90:91], v[90:91], v[170:171]
	v_pk_mul_f32 v[92:93], v[92:93], v[174:175]
	v_cvt_f32_ubyte0_e32 v0, v176
	v_cvt_f32_ubyte1_e32 v171, v176
	v_cvt_f32_ubyte2_e32 v174, v176
	v_cvt_f32_ubyte3_e32 v175, v176
	v_rcp_iflag_f32_e32 v170, v0
	v_rcp_iflag_f32_e32 v171, v171
	v_rcp_iflag_f32_e32 v174, v174
	v_rcp_iflag_f32_e32 v175, v175
	v_cvt_f32_ubyte0_e32 v176, v177
	v_cvt_f32_ubyte1_e32 v178, v177
	v_cvt_f32_ubyte2_e32 v179, v177
	v_cvt_f32_ubyte3_e32 v180, v177
	v_rcp_iflag_f32_e32 v176, v176
	v_rcp_iflag_f32_e32 v177, v178
	v_rcp_iflag_f32_e32 v178, v179
	v_rcp_iflag_f32_e32 v179, v180
	v_cvt_f32_ubyte3_e32 v181, v172
	v_cvt_f32_ubyte2_e32 v180, v172
	v_cvt_f32_ubyte1_e32 v183, v172
	v_cvt_f32_ubyte0_e32 v182, v172
	v_pk_mul_f32 v[170:171], v[170:171], v[182:183]
	v_pk_mul_f32 v[174:175], v[174:175], v[180:181]
	v_pk_mul_f32 v[86:87], v[86:87], v[170:171]
	v_pk_mul_f32 v[88:89], v[88:89], v[174:175]
	v_cvt_f32_ubyte3_e32 v171, v173
	v_cvt_f32_ubyte2_e32 v170, v173
	v_cvt_f32_ubyte1_e32 v175, v173
	v_cvt_f32_ubyte0_e32 v174, v173
	v_pk_mul_f32 v[172:173], v[176:177], v[174:175]
	v_pk_mul_f32 v[170:171], v[178:179], v[170:171]
	v_pk_mul_f32 v[82:83], v[82:83], v[172:173]
	v_pk_mul_f32 v[84:85], v[84:85], v[170:171]
	v_cvt_f32_ubyte0_e32 v0, v166
	v_cvt_f32_ubyte1_e32 v170, v166
	v_cvt_f32_ubyte2_e32 v171, v166
	v_cvt_f32_ubyte3_e32 v172, v166
	v_cvt_f32_ubyte0_e32 v173, v167
	v_cvt_f32_ubyte1_e32 v174, v167
	v_cvt_f32_ubyte2_e32 v175, v167
	v_cvt_f32_ubyte3_e32 v176, v167
	v_rcp_iflag_f32_e32 v166, v0
	v_rcp_iflag_f32_e32 v167, v170
	v_rcp_iflag_f32_e32 v170, v171
	v_rcp_iflag_f32_e32 v171, v172
	v_rcp_iflag_f32_e32 v172, v173
	v_rcp_iflag_f32_e32 v173, v174
	v_rcp_iflag_f32_e32 v174, v175
	v_rcp_iflag_f32_e32 v175, v176
	v_cvt_f32_ubyte3_e32 v177, v162
	v_cvt_f32_ubyte2_e32 v176, v162
	v_cvt_f32_ubyte1_e32 v179, v162
	v_cvt_f32_ubyte0_e32 v178, v162
	v_pk_mul_f32 v[166:167], v[166:167], v[178:179]
	v_pk_mul_f32 v[170:171], v[170:171], v[176:177]
	v_pk_mul_f32 v[78:79], v[78:79], v[166:167]
	v_pk_mul_f32 v[80:81], v[80:81], v[170:171]
	v_cvt_f32_ubyte3_e32 v167, v163
	v_cvt_f32_ubyte2_e32 v166, v163
	v_cvt_f32_ubyte1_e32 v171, v163
	v_cvt_f32_ubyte0_e32 v170, v163
	v_pk_mul_f32 v[162:163], v[172:173], v[170:171]
	v_pk_mul_f32 v[166:167], v[174:175], v[166:167]
	v_pk_mul_f32 v[74:75], v[74:75], v[162:163]
	v_pk_mul_f32 v[76:77], v[76:77], v[166:167]
	v_cvt_f32_ubyte0_e32 v0, v168
	v_cvt_f32_ubyte1_e32 v163, v168
	v_cvt_f32_ubyte2_e32 v166, v168
	v_cvt_f32_ubyte3_e32 v167, v168
	v_rcp_iflag_f32_e32 v162, v0
	v_rcp_iflag_f32_e32 v163, v163
	v_rcp_iflag_f32_e32 v166, v166
	v_rcp_iflag_f32_e32 v167, v167
	v_cvt_f32_ubyte0_e32 v168, v169
	v_cvt_f32_ubyte1_e32 v170, v169
	v_cvt_f32_ubyte2_e32 v171, v169
	v_cvt_f32_ubyte3_e32 v172, v169
	v_rcp_iflag_f32_e32 v168, v168
	v_rcp_iflag_f32_e32 v169, v170
	v_rcp_iflag_f32_e32 v170, v171
	v_rcp_iflag_f32_e32 v171, v172
	v_cvt_f32_ubyte3_e32 v173, v164
	v_cvt_f32_ubyte2_e32 v172, v164
	v_cvt_f32_ubyte1_e32 v175, v164
	v_cvt_f32_ubyte0_e32 v174, v164
	v_pk_mul_f32 v[162:163], v[162:163], v[174:175]
	v_pk_mul_f32 v[166:167], v[166:167], v[172:173]
	v_pk_mul_f32 v[70:71], v[70:71], v[162:163]
	v_pk_mul_f32 v[72:73], v[72:73], v[166:167]
	v_cvt_f32_ubyte3_e32 v163, v165
	v_cvt_f32_ubyte2_e32 v162, v165
	v_cvt_f32_ubyte1_e32 v167, v165
	v_cvt_f32_ubyte0_e32 v166, v165
	v_pk_mul_f32 v[164:165], v[168:169], v[166:167]
	v_pk_mul_f32 v[162:163], v[170:171], v[162:163]
	v_pk_mul_f32 v[66:67], v[66:67], v[164:165]
	v_pk_mul_f32 v[68:69], v[68:69], v[162:163]
	s_waitcnt vmcnt(6)
;     __device__ __forceinline__ void mid(Acc& acc, const Unit& u, int s, int wr, int wc, int fr, int fq) const {
;     ...
;         for (int i = 0; i < 8; ++i) { const int ai = i >> 2, m = i & 3;
; #pragma unroll
;             for (int bj = 0; bj < 2; ++bj) {
;                 const u32x4 ga = G[i][0], gb = G[i][1];
;                 const u32x2 wa = bj == 0 ? (u32x2){ga.x, ga.y} : (u32x2){ga.z, ga.w}, wb = bj == 0 ? (u32x2){gb.x, gb.y} : (u32x2){gb.z, gb.w};
;                 float fa[8], fb[8]; gate_unpack8(wa, fa); gate_unpack8(wb, fb);
; #pragma unroll
;                 for (int e = 0; e < 8; ++e) fa[e] = fa[e] * __builtin_amdgcn_rcpf(fb[e]);
;                 f32x4& v0 = acc[ai][bj][m][0]; f32x4& v1 = acc[ai][bj][m][1];
;                 v0[0] *= fa[0]; v0[1] *= fa[1]; v0[2] *= fa[2]; v0[3] *= fa[3]; v1[0] *= fa[4]; v1[1] *= fa[5]; v1[2] *= fa[6]; v1[3] *= fa[7]; }
;             __builtin_amdgcn_sched_barrier(0); }
	v_cvt_f32_ubyte0_e32 v0, v158
	v_cvt_f32_ubyte1_e32 v162, v158
	v_cvt_f32_ubyte2_e32 v163, v158
	v_cvt_f32_ubyte3_e32 v164, v158
	v_cvt_f32_ubyte0_e32 v165, v159
	v_cvt_f32_ubyte1_e32 v166, v159
	v_cvt_f32_ubyte2_e32 v167, v159
	v_cvt_f32_ubyte3_e32 v168, v159
	v_rcp_iflag_f32_e32 v158, v0
	v_rcp_iflag_f32_e32 v159, v162
	v_rcp_iflag_f32_e32 v162, v163
	v_rcp_iflag_f32_e32 v163, v164
	v_rcp_iflag_f32_e32 v164, v165
	v_rcp_iflag_f32_e32 v165, v166
	v_rcp_iflag_f32_e32 v166, v167
	v_rcp_iflag_f32_e32 v167, v168
	v_cvt_f32_ubyte3_e32 v169, v154
	v_cvt_f32_ubyte2_e32 v168, v154
	v_cvt_f32_ubyte1_e32 v171, v154
	v_cvt_f32_ubyte0_e32 v170, v154
	v_pk_mul_f32 v[158:159], v[158:159], v[170:171]
	v_pk_mul_f32 v[162:163], v[162:163], v[168:169]
	v_pk_mul_f32 v[62:63], v[62:63], v[158:159]
	v_pk_mul_f32 v[64:65], v[64:65], v[162:163]
	v_cvt_f32_ubyte3_e32 v159, v155
	v_cvt_f32_ubyte2_e32 v158, v155
	v_cvt_f32_ubyte1_e32 v163, v155
	v_cvt_f32_ubyte0_e32 v162, v155
	v_pk_mul_f32 v[154:155], v[164:165], v[162:163]
	v_pk_mul_f32 v[158:159], v[166:167], v[158:159]
	v_pk_mul_f32 v[58:59], v[58:59], v[154:155]
	v_pk_mul_f32 v[60:61], v[60:61], v[158:159]
	v_cvt_f32_ubyte0_e32 v0, v160
	v_cvt_f32_ubyte1_e32 v155, v160
	v_cvt_f32_ubyte2_e32 v158, v160
	v_cvt_f32_ubyte3_e32 v159, v160
	v_rcp_iflag_f32_e32 v154, v0
	v_rcp_iflag_f32_e32 v155, v155
	v_rcp_iflag_f32_e32 v158, v158
	v_rcp_iflag_f32_e32 v159, v159
	v_cvt_f32_ubyte0_e32 v160, v161
	v_cvt_f32_ubyte1_e32 v162, v161
	v_cvt_f32_ubyte2_e32 v163, v161
	v_cvt_f32_ubyte3_e32 v164, v161
	v_rcp_iflag_f32_e32 v160, v160
	v_rcp_iflag_f32_e32 v161, v162
	v_rcp_iflag_f32_e32 v162, v163
	v_rcp_iflag_f32_e32 v163, v164
	v_cvt_f32_ubyte3_e32 v165, v156
	v_cvt_f32_ubyte2_e32 v164, v156
	v_cvt_f32_ubyte1_e32 v167, v156
	v_cvt_f32_ubyte0_e32 v166, v156
	v_pk_mul_f32 v[154:155], v[154:155], v[166:167]
	v_pk_mul_f32 v[158:159], v[158:159], v[164:165]
	v_pk_mul_f32 v[54:55], v[54:55], v[154:155]
	v_pk_mul_f32 v[56:57], v[56:57], v[158:159]
	v_cvt_f32_ubyte3_e32 v155, v157
	v_cvt_f32_ubyte2_e32 v154, v157
	v_cvt_f32_ubyte1_e32 v159, v157
	v_cvt_f32_ubyte0_e32 v158, v157
	v_pk_mul_f32 v[156:157], v[160:161], v[158:159]
	v_pk_mul_f32 v[154:155], v[162:163], v[154:155]
	v_pk_mul_f32 v[50:51], v[50:51], v[156:157]
	v_pk_mul_f32 v[52:53], v[52:53], v[154:155]
	s_waitcnt vmcnt(4)
	v_cvt_f32_ubyte0_e32 v0, v150
	v_cvt_f32_ubyte1_e32 v154, v150
	v_cvt_f32_ubyte2_e32 v155, v150
	v_cvt_f32_ubyte3_e32 v156, v150
	v_cvt_f32_ubyte0_e32 v157, v151
	v_cvt_f32_ubyte1_e32 v158, v151
	v_cvt_f32_ubyte2_e32 v159, v151
	v_cvt_f32_ubyte3_e32 v160, v151
	v_rcp_iflag_f32_e32 v150, v0
	v_rcp_iflag_f32_e32 v151, v154
	v_rcp_iflag_f32_e32 v154, v155
	v_rcp_iflag_f32_e32 v155, v156
	v_rcp_iflag_f32_e32 v156, v157
	v_rcp_iflag_f32_e32 v157, v158
	v_rcp_iflag_f32_e32 v158, v159
	v_rcp_iflag_f32_e32 v159, v160
	v_cvt_f32_ubyte3_e32 v161, v146
	v_cvt_f32_ubyte2_e32 v160, v146
	v_cvt_f32_ubyte1_e32 v163, v146
	v_cvt_f32_ubyte0_e32 v162, v146
	v_pk_mul_f32 v[150:151], v[150:151], v[162:163]
	v_pk_mul_f32 v[154:155], v[154:155], v[160:161]
	v_pk_mul_f32 v[46:47], v[46:47], v[150:151]
	v_pk_mul_f32 v[48:49], v[48:49], v[154:155]
	v_cvt_f32_ubyte3_e32 v151, v147
	v_cvt_f32_ubyte2_e32 v150, v147
	v_cvt_f32_ubyte1_e32 v155, v147
	v_cvt_f32_ubyte0_e32 v154, v147
	v_pk_mul_f32 v[146:147], v[156:157], v[154:155]
	v_pk_mul_f32 v[150:151], v[158:159], v[150:151]
	v_pk_mul_f32 v[42:43], v[42:43], v[146:147]
	v_pk_mul_f32 v[44:45], v[44:45], v[150:151]
	v_cvt_f32_ubyte0_e32 v0, v152
	v_cvt_f32_ubyte1_e32 v147, v152
	v_cvt_f32_ubyte2_e32 v150, v152
	v_cvt_f32_ubyte3_e32 v151, v152
	v_rcp_iflag_f32_e32 v146, v0
	v_rcp_iflag_f32_e32 v147, v147
	v_rcp_iflag_f32_e32 v150, v150
	v_rcp_iflag_f32_e32 v151, v151
	v_cvt_f32_ubyte0_e32 v152, v153
	v_cvt_f32_ubyte1_e32 v154, v153
	v_cvt_f32_ubyte2_e32 v155, v153
	v_cvt_f32_ubyte3_e32 v156, v153
	v_rcp_iflag_f32_e32 v152, v152
	v_rcp_iflag_f32_e32 v153, v154
	v_rcp_iflag_f32_e32 v154, v155
	v_rcp_iflag_f32_e32 v155, v156
	v_cvt_f32_ubyte3_e32 v157, v148
	v_cvt_f32_ubyte2_e32 v156, v148
	v_cvt_f32_ubyte1_e32 v159, v148
	v_cvt_f32_ubyte0_e32 v158, v148
	v_pk_mul_f32 v[146:147], v[146:147], v[158:159]
	v_pk_mul_f32 v[150:151], v[150:151], v[156:157]
	v_pk_mul_f32 v[38:39], v[38:39], v[146:147]
	v_pk_mul_f32 v[40:41], v[40:41], v[150:151]
	v_cvt_f32_ubyte3_e32 v147, v149
	v_cvt_f32_ubyte2_e32 v146, v149
	v_cvt_f32_ubyte1_e32 v151, v149
	v_cvt_f32_ubyte0_e32 v150, v149
	v_pk_mul_f32 v[148:149], v[152:153], v[150:151]
	v_pk_mul_f32 v[146:147], v[154:155], v[146:147]
	v_pk_mul_f32 v[34:35], v[34:35], v[148:149]
	v_pk_mul_f32 v[36:37], v[36:37], v[146:147]
	s_waitcnt vmcnt(2)
;     __device__ __forceinline__ void mid(Acc& acc, const Unit& u, int s, int wr, int wc, int fr, int fq) const {
;     ...
;         for (int i = 0; i < 8; ++i) { const int ai = i >> 2, m = i & 3;
; #pragma unroll
;             for (int bj = 0; bj < 2; ++bj) {
;                 const u32x4 ga = G[i][0], gb = G[i][1];
;                 const u32x2 wa = bj == 0 ? (u32x2){ga.x, ga.y} : (u32x2){ga.z, ga.w}, wb = bj == 0 ? (u32x2){gb.x, gb.y} : (u32x2){gb.z, gb.w};
;                 float fa[8], fb[8]; gate_unpack8(wa, fa); gate_unpack8(wb, fb);
; #pragma unroll
;                 for (int e = 0; e < 8; ++e) fa[e] = fa[e] * __builtin_amdgcn_rcpf(fb[e]);
;                 f32x4& v0 = acc[ai][bj][m][0]; f32x4& v1 = acc[ai][bj][m][1];
;                 v0[0] *= fa[0]; v0[1] *= fa[1]; v0[2] *= fa[2]; v0[3] *= fa[3]; v1[0] *= fa[4]; v1[1] *= fa[5]; v1[2] *= fa[6]; v1[3] *= fa[7]; }
;             __builtin_amdgcn_sched_barrier(0); }
	v_cvt_f32_ubyte0_e32 v0, v142
	v_cvt_f32_ubyte1_e32 v146, v142
	v_cvt_f32_ubyte2_e32 v147, v142
	v_cvt_f32_ubyte3_e32 v148, v142
	v_cvt_f32_ubyte0_e32 v149, v143
	v_cvt_f32_ubyte1_e32 v150, v143
	v_cvt_f32_ubyte2_e32 v151, v143
	v_cvt_f32_ubyte3_e32 v152, v143
	v_rcp_iflag_f32_e32 v142, v0
	v_rcp_iflag_f32_e32 v143, v146
	v_rcp_iflag_f32_e32 v146, v147
	v_rcp_iflag_f32_e32 v147, v148
	v_rcp_iflag_f32_e32 v148, v149
	v_rcp_iflag_f32_e32 v149, v150
	v_rcp_iflag_f32_e32 v150, v151
	v_rcp_iflag_f32_e32 v151, v152
	v_cvt_f32_ubyte3_e32 v153, v138
	v_cvt_f32_ubyte2_e32 v152, v138
	v_cvt_f32_ubyte1_e32 v155, v138
	v_cvt_f32_ubyte0_e32 v154, v138
	v_pk_mul_f32 v[142:143], v[142:143], v[154:155]
	v_pk_mul_f32 v[146:147], v[146:147], v[152:153]
	v_pk_mul_f32 v[30:31], v[30:31], v[142:143]
	v_pk_mul_f32 v[32:33], v[32:33], v[146:147]
	v_cvt_f32_ubyte3_e32 v143, v139
	v_cvt_f32_ubyte2_e32 v142, v139
	v_cvt_f32_ubyte1_e32 v147, v139
	v_cvt_f32_ubyte0_e32 v146, v139
	v_pk_mul_f32 v[138:139], v[148:149], v[146:147]
	v_pk_mul_f32 v[142:143], v[150:151], v[142:143]
	v_pk_mul_f32 v[22:23], v[22:23], v[138:139]
	v_pk_mul_f32 v[24:25], v[24:25], v[142:143]
	v_cvt_f32_ubyte0_e32 v0, v144
	v_cvt_f32_ubyte1_e32 v139, v144
	v_cvt_f32_ubyte2_e32 v142, v144
	v_cvt_f32_ubyte3_e32 v143, v144
	v_rcp_iflag_f32_e32 v138, v0
	v_rcp_iflag_f32_e32 v139, v139
	v_rcp_iflag_f32_e32 v142, v142
	v_rcp_iflag_f32_e32 v143, v143
	v_cvt_f32_ubyte0_e32 v144, v145
	v_cvt_f32_ubyte1_e32 v146, v145
	v_cvt_f32_ubyte2_e32 v147, v145
	v_cvt_f32_ubyte3_e32 v148, v145
	v_rcp_iflag_f32_e32 v144, v144
	v_rcp_iflag_f32_e32 v145, v146
	v_rcp_iflag_f32_e32 v146, v147
	v_rcp_iflag_f32_e32 v147, v148
	v_cvt_f32_ubyte3_e32 v149, v140
	v_cvt_f32_ubyte2_e32 v148, v140
	v_cvt_f32_ubyte1_e32 v151, v140
	v_cvt_f32_ubyte0_e32 v150, v140
	v_pk_mul_f32 v[138:139], v[138:139], v[150:151]
	v_pk_mul_f32 v[142:143], v[142:143], v[148:149]
	v_pk_mul_f32 v[26:27], v[26:27], v[138:139]
	v_pk_mul_f32 v[28:29], v[28:29], v[142:143]
	v_cvt_f32_ubyte3_e32 v139, v141
	v_cvt_f32_ubyte2_e32 v138, v141
	v_cvt_f32_ubyte1_e32 v143, v141
	v_cvt_f32_ubyte0_e32 v142, v141
	v_pk_mul_f32 v[140:141], v[144:145], v[142:143]
	v_pk_mul_f32 v[138:139], v[146:147], v[138:139]
	v_pk_mul_f32 v[18:19], v[18:19], v[140:141]
	v_pk_mul_f32 v[20:21], v[20:21], v[138:139]
	s_waitcnt vmcnt(0)
	v_cvt_f32_ubyte0_e32 v0, v134
	v_cvt_f32_ubyte1_e32 v138, v134
	v_cvt_f32_ubyte2_e32 v139, v134
	v_cvt_f32_ubyte3_e32 v140, v134
	v_cvt_f32_ubyte0_e32 v141, v135
	v_cvt_f32_ubyte1_e32 v142, v135
	v_cvt_f32_ubyte2_e32 v143, v135
	v_cvt_f32_ubyte3_e32 v144, v135
	v_rcp_iflag_f32_e32 v134, v0
	v_rcp_iflag_f32_e32 v135, v138
	v_rcp_iflag_f32_e32 v138, v139
	v_rcp_iflag_f32_e32 v139, v140
	v_rcp_iflag_f32_e32 v140, v141
	v_rcp_iflag_f32_e32 v141, v142
	v_rcp_iflag_f32_e32 v142, v143
	v_rcp_iflag_f32_e32 v143, v144
	v_cvt_f32_ubyte3_e32 v145, v130
	v_cvt_f32_ubyte2_e32 v144, v130
	v_cvt_f32_ubyte1_e32 v147, v130
	v_cvt_f32_ubyte0_e32 v146, v130
	v_pk_mul_f32 v[134:135], v[134:135], v[146:147]
	v_pk_mul_f32 v[138:139], v[138:139], v[144:145]
	v_pk_mul_f32 v[14:15], v[14:15], v[134:135]
	v_pk_mul_f32 v[16:17], v[16:17], v[138:139]
	v_cvt_f32_ubyte3_e32 v135, v131
	v_cvt_f32_ubyte2_e32 v134, v131
	v_cvt_f32_ubyte1_e32 v139, v131
	v_cvt_f32_ubyte0_e32 v138, v131
	v_pk_mul_f32 v[130:131], v[140:141], v[138:139]
	v_pk_mul_f32 v[134:135], v[142:143], v[134:135]
	v_pk_mul_f32 v[6:7], v[6:7], v[130:131]
	v_pk_mul_f32 v[8:9], v[8:9], v[134:135]
	v_cvt_f32_ubyte0_e32 v0, v136
	v_cvt_f32_ubyte1_e32 v131, v136
	v_cvt_f32_ubyte2_e32 v134, v136
	v_cvt_f32_ubyte3_e32 v135, v136
	v_rcp_iflag_f32_e32 v130, v0
	v_rcp_iflag_f32_e32 v131, v131
	v_rcp_iflag_f32_e32 v134, v134
	v_rcp_iflag_f32_e32 v135, v135
	v_cvt_f32_ubyte0_e32 v136, v137
	v_cvt_f32_ubyte1_e32 v138, v137
	v_cvt_f32_ubyte2_e32 v139, v137
	v_cvt_f32_ubyte3_e32 v140, v137
	v_rcp_iflag_f32_e32 v136, v136
	v_rcp_iflag_f32_e32 v137, v138
	v_rcp_iflag_f32_e32 v138, v139
	v_rcp_iflag_f32_e32 v139, v140
	v_cvt_f32_ubyte3_e32 v141, v132
	v_cvt_f32_ubyte2_e32 v140, v132
	v_cvt_f32_ubyte1_e32 v143, v132
	v_cvt_f32_ubyte0_e32 v142, v132
	v_pk_mul_f32 v[130:131], v[130:131], v[142:143]
	v_pk_mul_f32 v[134:135], v[134:135], v[140:141]
	v_pk_mul_f32 v[10:11], v[10:11], v[130:131]
	v_pk_mul_f32 v[12:13], v[12:13], v[134:135]
	v_cvt_f32_ubyte3_e32 v131, v133
	v_cvt_f32_ubyte2_e32 v130, v133
	v_cvt_f32_ubyte1_e32 v135, v133
	v_cvt_f32_ubyte0_e32 v134, v133
	v_pk_mul_f32 v[132:133], v[136:137], v[134:135]
	v_pk_mul_f32 v[130:131], v[138:139], v[130:131]
	v_pk_mul_f32 v[2:3], v[2:3], v[132:133]
	v_pk_mul_f32 v[4:5], v[4:5], v[130:131]
